# sample-row GEMM K loops (sgemm_wide x2, sgemm_phase) software-pipelined: 24-32 loads in flight instead of load-wait-mfma
# speedup vs baseline: 1.0096x; 1.0066x over previous
.LBB0_505:
	s_ashr_i32 s11, s3, 31
	s_lshr_b32 s11, s11, 27
	s_add_i32 s11, s3, s11
	s_ashr_i32 s20, s11, 5
	s_lshl_b32 s11, s20, 6
	s_lshl_b32 s21, s20, 10
	s_lshl_b32 s20, s3, 5
	s_sub_i32 s20, s20, s21
	s_ashr_i32 s39, s20, 8
	s_mul_i32 s40, s39, s73
	s_ashr_i32 s41, s40, 31
	v_add_u32_e32 v2, s11, v61
	s_lshl_b64 s[40:41], s[40:41], 1
	v_ashrrev_i32_e32 v3, 31, v2
	v_mov_b64_e32 v[0:1], s[40:41]
	v_mad_u64_u32 v[0:1], s[40:41], s4, v2, v[0:1]
	v_mul_lo_u32 v3, s4, v3
	v_mul_lo_u32 v2, s5, v2
	v_add3_u32 v1, v2, v1, v3
	v_lshl_add_u64 v[48:49], v[36:37], 0, v[0:1]
	v_lshl_add_u64 v[50:51], v[38:39], 0, v[0:1]
	v_lshl_add_u64 v[52:53], v[40:41], 0, v[0:1]
	v_lshl_add_u64 v[54:55], v[42:43], 0, v[0:1]
	v_subrev_u32_e32 v0, s21, v62
	v_ashrrev_i32_e32 v1, 31, v0
	v_mad_u64_u32 v[56:57], s[40:41], s8, v0, v[44:45]
	v_mul_lo_u32 v1, s8, v1
	v_mul_lo_u32 v2, s9, v0
	v_mad_u64_u32 v[58:59], s[40:41], s8, v0, v[46:47]
	v_mov_b32_e32 v0, 0
	v_add3_u32 v57, v2, v57, v1
	v_add3_u32 v59, v2, v59, v1
	s_mov_b32 s21, 0
	v_mov_b32_e32 v1, v0
	v_mov_b32_e32 v2, v0
	v_mov_b32_e32 v3, v0
	v_mov_b32_e32 v4, v0
	v_mov_b32_e32 v5, v0
	v_mov_b32_e32 v6, v0
	v_mov_b32_e32 v7, v0
	v_mov_b32_e32 v8, v0
	v_mov_b32_e32 v9, v0
	v_mov_b32_e32 v10, v0
	v_mov_b32_e32 v11, v0
	v_mov_b32_e32 v12, v0
	v_mov_b32_e32 v13, v0
	v_mov_b32_e32 v14, v0
	v_mov_b32_e32 v15, v0
	v_mov_b32_e32 v16, v0
	v_mov_b32_e32 v17, v0
	v_mov_b32_e32 v18, v0
	v_mov_b32_e32 v19, v0
	v_mov_b32_e32 v20, v0
	v_mov_b32_e32 v21, v0
	v_mov_b32_e32 v22, v0
	v_mov_b32_e32 v23, v0
	v_mov_b32_e32 v24, v0
	v_mov_b32_e32 v25, v0
	v_mov_b32_e32 v26, v0
	v_mov_b32_e32 v27, v0
	v_mov_b32_e32 v28, v0
	v_mov_b32_e32 v29, v0
	v_mov_b32_e32 v30, v0
	v_mov_b32_e32 v31, v0
	s_and_b32 vcc_lo, s38, 0x7f
	s_cbranch_scc1 .Lsgp_orig
	v_lshl_add_u64 v[224:225], v[48:49], 0, v[34:35]
	v_lshl_add_u64 v[226:227], v[50:51], 0, v[34:35]
	v_lshl_add_u64 v[228:229], v[52:53], 0, v[34:35]
	v_lshl_add_u64 v[230:231], v[54:55], 0, v[34:35]
	v_lshl_add_u64 v[232:233], v[56:57], 0, v[34:35]
	v_lshl_add_u64 v[234:235], v[58:59], 0, v[34:35]
	global_load_dwordx4 v[66:69], v[232:233], off
	global_load_dwordx4 v[74:77], v[224:225], off
	global_load_dwordx4 v[70:73], v[234:235], off
	global_load_dwordx4 v[78:81], v[226:227], off
	global_load_dwordx4 v[82:85], v[228:229], off
	global_load_dwordx4 v[86:89], v[230:231], off
	global_load_dwordx4 v[90:93], v[232:233], off offset:64
	global_load_dwordx4 v[98:101], v[224:225], off offset:64
	global_load_dwordx4 v[94:97], v[234:235], off offset:64
	global_load_dwordx4 v[102:105], v[226:227], off offset:64
	global_load_dwordx4 v[106:109], v[228:229], off offset:64
	global_load_dwordx4 v[110:113], v[230:231], off offset:64
	global_load_dwordx4 v[114:117], v[232:233], off offset:128
	global_load_dwordx4 v[122:125], v[224:225], off offset:128
	global_load_dwordx4 v[118:121], v[234:235], off offset:128
	global_load_dwordx4 v[188:191], v[226:227], off offset:128
	global_load_dwordx4 v[192:195], v[228:229], off offset:128
	global_load_dwordx4 v[196:199], v[230:231], off offset:128
	global_load_dwordx4 v[200:203], v[232:233], off offset:192
	global_load_dwordx4 v[208:211], v[224:225], off offset:192
	global_load_dwordx4 v[204:207], v[234:235], off offset:192
	global_load_dwordx4 v[212:215], v[226:227], off offset:192
	global_load_dwordx4 v[216:219], v[228:229], off offset:192
	global_load_dwordx4 v[220:223], v[230:231], off offset:192
	s_movk_i32 s21, 0x80
.Lsgp_loop:
	s_cmp_ge_u32 s21, s38
	s_cbranch_scc1 .Lsgp_final
	s_waitcnt vmcnt(18)
	v_mfma_f32_16x16x32_bf16 v[28:31], v[66:69], v[74:77], v[28:31]
	v_mfma_f32_16x16x32_bf16 v[24:27], v[70:73], v[74:77], v[24:27]
	v_mfma_f32_16x16x32_bf16 v[20:23], v[66:69], v[78:81], v[20:23]
	v_mfma_f32_16x16x32_bf16 v[16:19], v[70:73], v[78:81], v[16:19]
	v_mfma_f32_16x16x32_bf16 v[12:15], v[66:69], v[82:85], v[12:15]
	v_mfma_f32_16x16x32_bf16 v[8:11], v[70:73], v[82:85], v[8:11]
	v_mfma_f32_16x16x32_bf16 v[4:7], v[66:69], v[86:89], v[4:7]
	v_mfma_f32_16x16x32_bf16 v[0:3], v[70:73], v[86:89], v[0:3]
	global_load_dwordx4 v[66:69], v[232:233], off offset:256
	global_load_dwordx4 v[74:77], v[224:225], off offset:256
	global_load_dwordx4 v[70:73], v[234:235], off offset:256
	global_load_dwordx4 v[78:81], v[226:227], off offset:256
	global_load_dwordx4 v[82:85], v[228:229], off offset:256
	global_load_dwordx4 v[86:89], v[230:231], off offset:256
	s_waitcnt vmcnt(18)
	v_mfma_f32_16x16x32_bf16 v[28:31], v[90:93], v[98:101], v[28:31]
	v_mfma_f32_16x16x32_bf16 v[24:27], v[94:97], v[98:101], v[24:27]
	v_mfma_f32_16x16x32_bf16 v[20:23], v[90:93], v[102:105], v[20:23]
	v_mfma_f32_16x16x32_bf16 v[16:19], v[94:97], v[102:105], v[16:19]
	v_mfma_f32_16x16x32_bf16 v[12:15], v[90:93], v[106:109], v[12:15]
	v_mfma_f32_16x16x32_bf16 v[8:11], v[94:97], v[106:109], v[8:11]
	v_mfma_f32_16x16x32_bf16 v[4:7], v[90:93], v[110:113], v[4:7]
	v_mfma_f32_16x16x32_bf16 v[0:3], v[94:97], v[110:113], v[0:3]
	global_load_dwordx4 v[90:93], v[232:233], off offset:320
	global_load_dwordx4 v[98:101], v[224:225], off offset:320
	global_load_dwordx4 v[94:97], v[234:235], off offset:320
	global_load_dwordx4 v[102:105], v[226:227], off offset:320
	global_load_dwordx4 v[106:109], v[228:229], off offset:320
	global_load_dwordx4 v[110:113], v[230:231], off offset:320
	s_waitcnt vmcnt(18)
	v_mfma_f32_16x16x32_bf16 v[28:31], v[114:117], v[122:125], v[28:31]
	v_mfma_f32_16x16x32_bf16 v[24:27], v[118:121], v[122:125], v[24:27]
	v_mfma_f32_16x16x32_bf16 v[20:23], v[114:117], v[188:191], v[20:23]
	v_mfma_f32_16x16x32_bf16 v[16:19], v[118:121], v[188:191], v[16:19]
	v_mfma_f32_16x16x32_bf16 v[12:15], v[114:117], v[192:195], v[12:15]
	v_mfma_f32_16x16x32_bf16 v[8:11], v[118:121], v[192:195], v[8:11]
	v_mfma_f32_16x16x32_bf16 v[4:7], v[114:117], v[196:199], v[4:7]
	v_mfma_f32_16x16x32_bf16 v[0:3], v[118:121], v[196:199], v[0:3]
	global_load_dwordx4 v[114:117], v[232:233], off offset:384
	global_load_dwordx4 v[122:125], v[224:225], off offset:384
	global_load_dwordx4 v[118:121], v[234:235], off offset:384
	global_load_dwordx4 v[188:191], v[226:227], off offset:384
	global_load_dwordx4 v[192:195], v[228:229], off offset:384
	global_load_dwordx4 v[196:199], v[230:231], off offset:384
	s_waitcnt vmcnt(18)
	v_mfma_f32_16x16x32_bf16 v[28:31], v[200:203], v[208:211], v[28:31]
	v_mfma_f32_16x16x32_bf16 v[24:27], v[204:207], v[208:211], v[24:27]
	v_mfma_f32_16x16x32_bf16 v[20:23], v[200:203], v[212:215], v[20:23]
	v_mfma_f32_16x16x32_bf16 v[16:19], v[204:207], v[212:215], v[16:19]
	v_mfma_f32_16x16x32_bf16 v[12:15], v[200:203], v[216:219], v[12:15]
	v_mfma_f32_16x16x32_bf16 v[8:11], v[204:207], v[216:219], v[8:11]
	v_mfma_f32_16x16x32_bf16 v[4:7], v[200:203], v[220:223], v[4:7]
	v_mfma_f32_16x16x32_bf16 v[0:3], v[204:207], v[220:223], v[0:3]
	global_load_dwordx4 v[200:203], v[232:233], off offset:448
	global_load_dwordx4 v[208:211], v[224:225], off offset:448
	global_load_dwordx4 v[204:207], v[234:235], off offset:448
	global_load_dwordx4 v[212:215], v[226:227], off offset:448
	global_load_dwordx4 v[216:219], v[228:229], off offset:448
	global_load_dwordx4 v[220:223], v[230:231], off offset:448
	v_lshl_add_u64 v[224:225], 64, 2, v[224:225]
	v_lshl_add_u64 v[226:227], 64, 2, v[226:227]
	v_lshl_add_u64 v[228:229], 64, 2, v[228:229]
	v_lshl_add_u64 v[230:231], 64, 2, v[230:231]
	v_lshl_add_u64 v[232:233], 64, 2, v[232:233]
	v_lshl_add_u64 v[234:235], 64, 2, v[234:235]
	s_addk_i32 s21, 0x80
	s_branch .Lsgp_loop
.Lsgp_final:
	s_waitcnt vmcnt(18)
	v_mfma_f32_16x16x32_bf16 v[28:31], v[66:69], v[74:77], v[28:31]
	v_mfma_f32_16x16x32_bf16 v[24:27], v[70:73], v[74:77], v[24:27]
	v_mfma_f32_16x16x32_bf16 v[20:23], v[66:69], v[78:81], v[20:23]
	v_mfma_f32_16x16x32_bf16 v[16:19], v[70:73], v[78:81], v[16:19]
	v_mfma_f32_16x16x32_bf16 v[12:15], v[66:69], v[82:85], v[12:15]
	v_mfma_f32_16x16x32_bf16 v[8:11], v[70:73], v[82:85], v[8:11]
	v_mfma_f32_16x16x32_bf16 v[4:7], v[66:69], v[86:89], v[4:7]
	v_mfma_f32_16x16x32_bf16 v[0:3], v[70:73], v[86:89], v[0:3]
	s_waitcnt vmcnt(12)
	v_mfma_f32_16x16x32_bf16 v[28:31], v[90:93], v[98:101], v[28:31]
	v_mfma_f32_16x16x32_bf16 v[24:27], v[94:97], v[98:101], v[24:27]
	v_mfma_f32_16x16x32_bf16 v[20:23], v[90:93], v[102:105], v[20:23]
	v_mfma_f32_16x16x32_bf16 v[16:19], v[94:97], v[102:105], v[16:19]
	v_mfma_f32_16x16x32_bf16 v[12:15], v[90:93], v[106:109], v[12:15]
	v_mfma_f32_16x16x32_bf16 v[8:11], v[94:97], v[106:109], v[8:11]
	v_mfma_f32_16x16x32_bf16 v[4:7], v[90:93], v[110:113], v[4:7]
	v_mfma_f32_16x16x32_bf16 v[0:3], v[94:97], v[110:113], v[0:3]
	s_waitcnt vmcnt(6)
	v_mfma_f32_16x16x32_bf16 v[28:31], v[114:117], v[122:125], v[28:31]
	v_mfma_f32_16x16x32_bf16 v[24:27], v[118:121], v[122:125], v[24:27]
	v_mfma_f32_16x16x32_bf16 v[20:23], v[114:117], v[188:191], v[20:23]
	v_mfma_f32_16x16x32_bf16 v[16:19], v[118:121], v[188:191], v[16:19]
	v_mfma_f32_16x16x32_bf16 v[12:15], v[114:117], v[192:195], v[12:15]
	v_mfma_f32_16x16x32_bf16 v[8:11], v[118:121], v[192:195], v[8:11]
	v_mfma_f32_16x16x32_bf16 v[4:7], v[114:117], v[196:199], v[4:7]
	v_mfma_f32_16x16x32_bf16 v[0:3], v[118:121], v[196:199], v[0:3]
	s_waitcnt vmcnt(0)
	v_mfma_f32_16x16x32_bf16 v[28:31], v[200:203], v[208:211], v[28:31]
	v_mfma_f32_16x16x32_bf16 v[24:27], v[204:207], v[208:211], v[24:27]
	v_mfma_f32_16x16x32_bf16 v[20:23], v[200:203], v[212:215], v[20:23]
	v_mfma_f32_16x16x32_bf16 v[16:19], v[204:207], v[212:215], v[16:19]
	v_mfma_f32_16x16x32_bf16 v[12:15], v[200:203], v[216:219], v[12:15]
	v_mfma_f32_16x16x32_bf16 v[8:11], v[204:207], v[216:219], v[8:11]
	v_mfma_f32_16x16x32_bf16 v[4:7], v[200:203], v[220:223], v[4:7]
	v_mfma_f32_16x16x32_bf16 v[0:3], v[204:207], v[220:223], v[0:3]
	s_nop 1
	s_branch .Lsgp_done
.Lsgp_orig:
.LBB0_506:
	v_lshl_add_u64 v[70:71], v[48:49], 0, v[34:35]
	v_lshl_add_u64 v[66:67], v[56:57], 0, v[34:35]
	v_lshl_add_u64 v[74:75], v[58:59], 0, v[34:35]
	global_load_dwordx4 v[66:69], v[66:67], off
	s_nop 0
	global_load_dwordx4 v[70:73], v[70:71], off
	v_lshl_add_u64 v[78:79], v[50:51], 0, v[34:35]
	global_load_dwordx4 v[74:77], v[74:75], off
	s_add_i32 s21, s21, 32
	v_lshl_add_u64 v[48:49], v[48:49], 0, 64
	v_lshl_add_u64 v[50:51], v[50:51], 0, 64
	v_lshl_add_u64 v[56:57], v[56:57], 0, 64
	s_cmp_ge_u32 s21, s38
	v_lshl_add_u64 v[58:59], v[58:59], 0, 64
	s_waitcnt vmcnt(0)
	v_mfma_f32_16x16x32_bf16 v[28:31], v[66:69], v[70:73], v[28:31]
	v_mfma_f32_16x16x32_bf16 v[24:27], v[74:77], v[70:73], v[24:27]
	global_load_dwordx4 v[70:73], v[78:79], off
	v_lshl_add_u64 v[78:79], v[52:53], 0, v[34:35]
	v_lshl_add_u64 v[52:53], v[52:53], 0, 64
	s_waitcnt vmcnt(0)
	v_mfma_f32_16x16x32_bf16 v[20:23], v[66:69], v[70:73], v[20:23]
	v_mfma_f32_16x16x32_bf16 v[16:19], v[74:77], v[70:73], v[16:19]
	global_load_dwordx4 v[70:73], v[78:79], off
	v_lshl_add_u64 v[78:79], v[54:55], 0, v[34:35]
	v_lshl_add_u64 v[54:55], v[54:55], 0, 64
	s_waitcnt vmcnt(0)
	v_mfma_f32_16x16x32_bf16 v[12:15], v[66:69], v[70:73], v[12:15]
	v_mfma_f32_16x16x32_bf16 v[8:11], v[74:77], v[70:73], v[8:11]
	global_load_dwordx4 v[70:73], v[78:79], off
	s_waitcnt vmcnt(0)
	v_mfma_f32_16x16x32_bf16 v[4:7], v[66:69], v[70:73], v[4:7]
	v_mfma_f32_16x16x32_bf16 v[0:3], v[74:77], v[70:73], v[0:3]
	s_cbranch_scc0 .LBB0_506
.Lsgp_done:
	ds_write_b128 v63, v[28:31]
	ds_write_b128 v63, v[24:27] offset:64
	ds_write_b128 v63, v[20:23] offset:2304
	ds_write_b128 v63, v[16:19] offset:2368
	ds_write_b128 v63, v[12:15] offset:4608
	ds_write_b128 v63, v[8:11] offset:4672
	ds_write_b128 v64, v[4:7]
	ds_write_b128 v64, v[0:3] offset:64
	s_waitcnt lgkmcnt(0)
	s_barrier
	ds_read_b128 v[0:3], v65
	ds_read_b128 v[4:7], v65 offset:9216
	ds_read_b128 v[8:11], v65 offset:18432
	s_ashr_i32 s21, s20, 31
	s_and_b64 vcc, exec, s[0:1]
	s_waitcnt lgkmcnt(2)
	v_pk_add_f32 v[2:3], v[2:3], 0 op_sel_hi:[1,0]
	v_pk_add_f32 v[12:13], v[0:1], 0 op_sel_hi:[1,0]
	s_waitcnt lgkmcnt(1)
	v_pk_add_f32 v[6:7], v[2:3], v[6:7]
	ds_read_b128 v[0:3], v65 offset:27648
	v_pk_add_f32 v[12:13], v[12:13], v[4:5]
	s_waitcnt lgkmcnt(1)
	v_pk_add_f32 v[10:11], v[6:7], v[10:11]
	ds_read_b128 v[4:7], v65 offset:36864
	v_pk_add_f32 v[8:9], v[12:13], v[8:9]
	s_waitcnt lgkmcnt(1)
	v_pk_add_f32 v[10:11], v[10:11], v[2:3]
	v_pk_add_f32 v[12:13], v[8:9], v[0:1]
	ds_read_b128 v[0:3], v65 offset:46080
	s_waitcnt lgkmcnt(1)
	v_pk_add_f32 v[14:15], v[10:11], v[6:7]
	ds_read_b128 v[6:9], v65 offset:55296
	v_pk_add_f32 v[4:5], v[12:13], v[4:5]
	ds_read_b128 v[10:13], v65 offset:64512
	s_waitcnt lgkmcnt(2)
	v_pk_add_f32 v[2:3], v[14:15], v[2:3]
	v_pk_add_f32 v[0:1], v[4:5], v[0:1]
	s_waitcnt lgkmcnt(1)
	v_pk_add_f32 v[2:3], v[2:3], v[8:9]
	v_pk_add_f32 v[4:5], v[0:1], v[6:7]
	s_waitcnt lgkmcnt(0)
	v_pk_add_f32 v[0:1], v[2:3], v[12:13]
	v_pk_add_f32 v[2:3], v[4:5], v[10:11]
	s_cbranch_vccz .LBB0_504
	v_lshl_add_u64 v[4:5], s[20:21], 2, v[32:33]
	global_load_dwordx4 v[4:7], v[4:5], off
	s_waitcnt vmcnt(0)
	v_pk_mul_f32 v[0:1], v[0:1], v[6:7]
	v_pk_mul_f32 v[2:3], v[2:3], v[4:5]
	s_branch .LBB0_504
